# hyena panel loops: fragment reads for the 3rd/4th s-chunk of each iteration go to spare registers and are issued four MFMAs before use (counted waits), instead of right before their MFMAs
# baseline (speedup 1.0000x reference)
; #define GAS __attribute__((address_space(1)))
; DI f32x16 mfma32(bf16x8 a, bf16x8 b, f32x16 c) { return __builtin_amdgcn_mfma_f32_32x32x16_bf16(a, b, c, 0, 0, 0); }
; DI void hyena_item(char* smem, const bf16_t* __restrict__ zin, const bf16_t* __restrict__ xg, const bf16_t* __restrict__ arr, float bias, bf16_t* __restrict__ zout, int tq, int tid) {
;     ...
;   for (int pnl = 0; pnl < 8; ++pnl) {
;     const char* zs = smem + ZOFF + (pnl & 1) * ZPB;
;     const bool more = (pnl + 1 < 8);
;     if (more) {
; #pragma unroll
;       for (int i = 0; i < 4; ++i) zr[i] = *(const GAS u32x4*)(zin + (size_t)(zb + 8 * i) * 2048 + (pnl + 1) * 256 + zc * 8);
;     }
;     __builtin_amdgcn_sched_barrier(0);
; #pragma unroll 4
;     for (int sc = 0; sc < 16; ++sc) {
;       const bf16x8 zf = *(const bf16x8*)(zs + r * ZSB + sc * 32 + h * 16);
;       const char* gp = gbase + (pnl * 256 + sc * 16) * 2;
; #pragma unroll
;       for (int i = 0; i < 4; ++i) {
;         const s16x4 g0 = *(const s16x4*)(gp - 64 * i), g1 = *(const s16x4*)(gp - 64 * i + 8);
;         const bf16x8 gf = __builtin_shufflevector(g0, g1, 0, 1, 2, 3, 4, 5, 6, 7);
;         acc[i] = mfma32(gf, zf, acc[i]);
;       }
;     }
;     if (more) {
;       char* zn = smem + ZOFF + ((pnl + 1) & 1) * ZPB;
; #pragma unroll
;       for (int i = 0; i < 4; ++i) *(u32x4*)(zn + (zb + 8 * i) * ZSB + zc * 16) = zr[i];
;     }
;     __syncthreads();
;   }
.LBB0_324:
	v_add_u32_e32 v96, s13, v148
	v_add_u32_e32 v83, s13, v147
	ds_read2_b64 v[92:95], v96 offset0:24 offset1:25
	ds_read_b128 v[160:163], v83
	ds_read_b128 v[164:167], v83 offset:32
	ds_read2_b64 v[168:171], v96 offset0:16 offset1:17
	ds_read2_b64 v[172:175], v96 offset0:8 offset1:9
	ds_read2_b64 v[176:179], v96 offset1:1
	s_waitcnt lgkmcnt(4)
	v_mfma_f32_32x32x16_bf16 v[50:65], v[92:95], v[160:163], v[50:65]
	ds_read2_b64 v[180:183], v96 offset0:12 offset1:13
	ds_read2_b64 v[192:195], v96 offset0:4 offset1:5
	s_addk_i32 s13, 0x80
	s_cmpk_lg_i32 s13, 0x200
	s_waitcnt lgkmcnt(4)
	v_mfma_f32_32x32x16_bf16 v[34:49], v[168:171], v[160:163], v[34:49]
	s_waitcnt lgkmcnt(3)
	v_mfma_f32_32x32x16_bf16 v[18:33], v[172:175], v[160:163], v[18:33]
	s_waitcnt lgkmcnt(2)
	v_mfma_f32_32x32x16_bf16 v[2:17], v[176:179], v[160:163], v[2:17]
	ds_read2_b64 v[160:163], v96 offset0:28 offset1:29
	ds_read2_b64 v[176:179], v96 offset0:20 offset1:21
	ds_read_b128 v[226:229], v83 offset:64
	ds_read2_b64 v[230:233], v96 offset0:32 offset1:33
	s_waitcnt lgkmcnt(3)
	v_mfma_f32_32x32x16_bf16 v[50:65], v[160:163], v[164:167], v[50:65]
	s_waitcnt lgkmcnt(2)
	v_mfma_f32_32x32x16_bf16 v[34:49], v[176:179], v[164:167], v[34:49]
	v_mfma_f32_32x32x16_bf16 v[18:33], v[180:183], v[164:167], v[18:33]
	v_mfma_f32_32x32x16_bf16 v[2:17], v[192:195], v[164:167], v[2:17]
	ds_read_b128 v[234:237], v83 offset:96
	ds_read2_b64 v[238:241], v96 offset0:36 offset1:37
	s_waitcnt lgkmcnt(2)
	v_mfma_f32_32x32x16_bf16 v[50:65], v[230:233], v[226:229], v[50:65]
	v_mfma_f32_32x32x16_bf16 v[34:49], v[92:95], v[226:229], v[34:49]
	v_mfma_f32_32x32x16_bf16 v[18:33], v[168:171], v[226:229], v[18:33]
	v_mfma_f32_32x32x16_bf16 v[2:17], v[172:175], v[226:229], v[2:17]
	s_waitcnt lgkmcnt(0)
	v_mfma_f32_32x32x16_bf16 v[50:65], v[238:241], v[234:237], v[50:65]
	v_mfma_f32_32x32x16_bf16 v[34:49], v[160:163], v[234:237], v[34:49]
	v_mfma_f32_32x32x16_bf16 v[18:33], v[176:179], v[234:237], v[18:33]
	v_mfma_f32_32x32x16_bf16 v[2:17], v[180:183], v[234:237], v[2:17]
	s_cbranch_scc1 .LBB0_324
	s_waitcnt vmcnt(3)
	ds_write_b128 v159, v[66:69] offset:37632
	s_waitcnt vmcnt(2)
	ds_write_b128 v159, v[70:73] offset:41856
	s_waitcnt vmcnt(1)
	ds_write_b128 v159, v[74:77] offset:46080
	s_waitcnt vmcnt(0)
	ds_write_b128 v159, v[78:81] offset:50304
	s_waitcnt lgkmcnt(0)
	s_barrier
	global_load_dwordx4 v[66:69], v[84:85], off offset:1024
	global_load_dwordx4 v[70:73], v[86:87], off offset:1024
	global_load_dwordx4 v[74:77], v[88:89], off offset:1024
	global_load_dwordx4 v[78:81], v[90:91], off offset:1024
	s_mov_b32 s13, 0
.LBB0_326:
	v_add_u32_e32 v96, s13, v149
	v_add_u32_e32 v83, s13, v150
	ds_read2_b64 v[92:95], v96 offset0:24 offset1:25
	ds_read_b128 v[160:163], v83
	ds_read_b128 v[164:167], v83 offset:32
	ds_read2_b64 v[168:171], v96 offset0:16 offset1:17
	ds_read2_b64 v[172:175], v96 offset0:8 offset1:9
	ds_read2_b64 v[176:179], v96 offset1:1
	s_waitcnt lgkmcnt(4)
	v_mfma_f32_32x32x16_bf16 v[50:65], v[92:95], v[160:163], v[50:65]
	ds_read2_b64 v[180:183], v96 offset0:12 offset1:13
	ds_read2_b64 v[192:195], v96 offset0:4 offset1:5
	s_addk_i32 s13, 0x80
	s_cmpk_lg_i32 s13, 0x200
	s_waitcnt lgkmcnt(4)
	v_mfma_f32_32x32x16_bf16 v[34:49], v[168:171], v[160:163], v[34:49]
	s_waitcnt lgkmcnt(3)
	v_mfma_f32_32x32x16_bf16 v[18:33], v[172:175], v[160:163], v[18:33]
	s_waitcnt lgkmcnt(2)
	v_mfma_f32_32x32x16_bf16 v[2:17], v[176:179], v[160:163], v[2:17]
	ds_read2_b64 v[160:163], v96 offset0:28 offset1:29
	ds_read2_b64 v[176:179], v96 offset0:20 offset1:21
	ds_read_b128 v[226:229], v83 offset:64
	ds_read2_b64 v[230:233], v96 offset0:32 offset1:33
	s_waitcnt lgkmcnt(3)
	v_mfma_f32_32x32x16_bf16 v[50:65], v[160:163], v[164:167], v[50:65]
	s_waitcnt lgkmcnt(2)
	v_mfma_f32_32x32x16_bf16 v[34:49], v[176:179], v[164:167], v[34:49]
	v_mfma_f32_32x32x16_bf16 v[18:33], v[180:183], v[164:167], v[18:33]
	v_mfma_f32_32x32x16_bf16 v[2:17], v[192:195], v[164:167], v[2:17]
	ds_read_b128 v[234:237], v83 offset:96
	ds_read2_b64 v[238:241], v96 offset0:36 offset1:37
	s_waitcnt lgkmcnt(2)
	v_mfma_f32_32x32x16_bf16 v[50:65], v[230:233], v[226:229], v[50:65]
	v_mfma_f32_32x32x16_bf16 v[34:49], v[92:95], v[226:229], v[34:49]
	v_mfma_f32_32x32x16_bf16 v[18:33], v[168:171], v[226:229], v[18:33]
	v_mfma_f32_32x32x16_bf16 v[2:17], v[172:175], v[226:229], v[2:17]
	s_waitcnt lgkmcnt(0)
	v_mfma_f32_32x32x16_bf16 v[50:65], v[238:241], v[234:237], v[50:65]
	v_mfma_f32_32x32x16_bf16 v[34:49], v[160:163], v[234:237], v[34:49]
	v_mfma_f32_32x32x16_bf16 v[18:33], v[176:179], v[234:237], v[18:33]
	v_mfma_f32_32x32x16_bf16 v[2:17], v[180:183], v[234:237], v[2:17]
	s_cbranch_scc1 .LBB0_326
	s_waitcnt vmcnt(3)
	ds_write_b128 v159, v[66:69] offset:20736
	s_waitcnt vmcnt(2)
	ds_write_b128 v159, v[70:73] offset:24960
	s_waitcnt vmcnt(1)
	ds_write_b128 v159, v[74:77] offset:29184
	s_waitcnt vmcnt(0)
	ds_write_b128 v159, v[78:81] offset:33408
	s_waitcnt lgkmcnt(0)
	s_barrier
	global_load_dwordx4 v[66:69], v[84:85], off offset:1536
	global_load_dwordx4 v[70:73], v[86:87], off offset:1536
	global_load_dwordx4 v[74:77], v[88:89], off offset:1536
	global_load_dwordx4 v[78:81], v[90:91], off offset:1536
	s_mov_b32 s13, 0
; #define GAS __attribute__((address_space(1)))
; DI f32x16 mfma32(bf16x8 a, bf16x8 b, f32x16 c) { return __builtin_amdgcn_mfma_f32_32x32x16_bf16(a, b, c, 0, 0, 0); }
; DI void hyena_item(char* smem, const bf16_t* __restrict__ zin, const bf16_t* __restrict__ xg, const bf16_t* __restrict__ arr, float bias, bf16_t* __restrict__ zout, int tq, int tid) {
;     ...
;   for (int pnl = 0; pnl < 8; ++pnl) {
;     const char* zs = smem + ZOFF + (pnl & 1) * ZPB;
;     const bool more = (pnl + 1 < 8);
;     if (more) {
; #pragma unroll
;       for (int i = 0; i < 4; ++i) zr[i] = *(const GAS u32x4*)(zin + (size_t)(zb + 8 * i) * 2048 + (pnl + 1) * 256 + zc * 8);
;     }
;     __builtin_amdgcn_sched_barrier(0);
; #pragma unroll 4
;     for (int sc = 0; sc < 16; ++sc) {
;       const bf16x8 zf = *(const bf16x8*)(zs + r * ZSB + sc * 32 + h * 16);
;       const char* gp = gbase + (pnl * 256 + sc * 16) * 2;
; #pragma unroll
;       for (int i = 0; i < 4; ++i) {
;         const s16x4 g0 = *(const s16x4*)(gp - 64 * i), g1 = *(const s16x4*)(gp - 64 * i + 8);
;         const bf16x8 gf = __builtin_shufflevector(g0, g1, 0, 1, 2, 3, 4, 5, 6, 7);
;         acc[i] = mfma32(gf, zf, acc[i]);
;       }
;     }
;     if (more) {
;       char* zn = smem + ZOFF + ((pnl + 1) & 1) * ZPB;
; #pragma unroll
;       for (int i = 0; i < 4; ++i) *(u32x4*)(zn + (zb + 8 * i) * ZSB + zc * 16) = zr[i];
;     }
;     __syncthreads();
;   }
.LBB0_328:
	v_add_u32_e32 v96, s13, v151
	v_add_u32_e32 v83, s13, v147
	ds_read2_b64 v[92:95], v96 offset0:24 offset1:25
	ds_read_b128 v[160:163], v83
	ds_read_b128 v[164:167], v83 offset:32
	ds_read2_b64 v[168:171], v96 offset0:16 offset1:17
	ds_read2_b64 v[172:175], v96 offset0:8 offset1:9
	ds_read2_b64 v[176:179], v96 offset1:1
	s_waitcnt lgkmcnt(4)
	v_mfma_f32_32x32x16_bf16 v[50:65], v[92:95], v[160:163], v[50:65]
	ds_read2_b64 v[180:183], v96 offset0:12 offset1:13
	ds_read2_b64 v[192:195], v96 offset0:4 offset1:5
	s_addk_i32 s13, 0x80
	s_cmpk_lg_i32 s13, 0x200
	s_waitcnt lgkmcnt(4)
	v_mfma_f32_32x32x16_bf16 v[34:49], v[168:171], v[160:163], v[34:49]
	s_waitcnt lgkmcnt(3)
	v_mfma_f32_32x32x16_bf16 v[18:33], v[172:175], v[160:163], v[18:33]
	s_waitcnt lgkmcnt(2)
	v_mfma_f32_32x32x16_bf16 v[2:17], v[176:179], v[160:163], v[2:17]
	ds_read2_b64 v[160:163], v96 offset0:28 offset1:29
	ds_read2_b64 v[176:179], v96 offset0:20 offset1:21
	ds_read_b128 v[226:229], v83 offset:64
	ds_read2_b64 v[230:233], v96 offset0:32 offset1:33
	s_waitcnt lgkmcnt(3)
	v_mfma_f32_32x32x16_bf16 v[50:65], v[160:163], v[164:167], v[50:65]
	s_waitcnt lgkmcnt(2)
	v_mfma_f32_32x32x16_bf16 v[34:49], v[176:179], v[164:167], v[34:49]
	v_mfma_f32_32x32x16_bf16 v[18:33], v[180:183], v[164:167], v[18:33]
	v_mfma_f32_32x32x16_bf16 v[2:17], v[192:195], v[164:167], v[2:17]
	ds_read_b128 v[234:237], v83 offset:96
	ds_read2_b64 v[238:241], v96 offset0:36 offset1:37
	s_waitcnt lgkmcnt(2)
	v_mfma_f32_32x32x16_bf16 v[50:65], v[230:233], v[226:229], v[50:65]
	v_mfma_f32_32x32x16_bf16 v[34:49], v[92:95], v[226:229], v[34:49]
	v_mfma_f32_32x32x16_bf16 v[18:33], v[168:171], v[226:229], v[18:33]
	v_mfma_f32_32x32x16_bf16 v[2:17], v[172:175], v[226:229], v[2:17]
	s_waitcnt lgkmcnt(0)
	v_mfma_f32_32x32x16_bf16 v[50:65], v[238:241], v[234:237], v[50:65]
	v_mfma_f32_32x32x16_bf16 v[34:49], v[160:163], v[234:237], v[34:49]
	v_mfma_f32_32x32x16_bf16 v[18:33], v[176:179], v[234:237], v[18:33]
	v_mfma_f32_32x32x16_bf16 v[2:17], v[180:183], v[234:237], v[2:17]
	s_cbranch_scc1 .LBB0_328
	s_waitcnt vmcnt(3)
	ds_write_b128 v159, v[66:69] offset:37632
	s_waitcnt vmcnt(2)
	ds_write_b128 v159, v[70:73] offset:41856
	s_waitcnt vmcnt(1)
	ds_write_b128 v159, v[74:77] offset:46080
	s_waitcnt vmcnt(0)
	ds_write_b128 v159, v[78:81] offset:50304
	s_waitcnt lgkmcnt(0)
	s_barrier
	global_load_dwordx4 v[66:69], v[84:85], off offset:2048
	global_load_dwordx4 v[70:73], v[86:87], off offset:2048
	global_load_dwordx4 v[74:77], v[88:89], off offset:2048
	global_load_dwordx4 v[78:81], v[90:91], off offset:2048
	s_mov_b32 s13, 0
.LBB0_330:
	v_add_u32_e32 v96, s13, v152
	v_add_u32_e32 v83, s13, v150
	ds_read2_b64 v[92:95], v96 offset0:24 offset1:25
	ds_read_b128 v[160:163], v83
	ds_read_b128 v[164:167], v83 offset:32
	ds_read2_b64 v[168:171], v96 offset0:16 offset1:17
	ds_read2_b64 v[172:175], v96 offset0:8 offset1:9
	ds_read2_b64 v[176:179], v96 offset1:1
	s_waitcnt lgkmcnt(4)
	v_mfma_f32_32x32x16_bf16 v[50:65], v[92:95], v[160:163], v[50:65]
	ds_read2_b64 v[180:183], v96 offset0:12 offset1:13
	ds_read2_b64 v[192:195], v96 offset0:4 offset1:5
	s_addk_i32 s13, 0x80
	s_cmpk_lg_i32 s13, 0x200
	s_waitcnt lgkmcnt(4)
	v_mfma_f32_32x32x16_bf16 v[34:49], v[168:171], v[160:163], v[34:49]
	s_waitcnt lgkmcnt(3)
	v_mfma_f32_32x32x16_bf16 v[18:33], v[172:175], v[160:163], v[18:33]
	s_waitcnt lgkmcnt(2)
	v_mfma_f32_32x32x16_bf16 v[2:17], v[176:179], v[160:163], v[2:17]
	ds_read2_b64 v[160:163], v96 offset0:28 offset1:29
	ds_read2_b64 v[176:179], v96 offset0:20 offset1:21
	ds_read_b128 v[226:229], v83 offset:64
	ds_read2_b64 v[230:233], v96 offset0:32 offset1:33
	s_waitcnt lgkmcnt(3)
	v_mfma_f32_32x32x16_bf16 v[50:65], v[160:163], v[164:167], v[50:65]
	s_waitcnt lgkmcnt(2)
	v_mfma_f32_32x32x16_bf16 v[34:49], v[176:179], v[164:167], v[34:49]
	v_mfma_f32_32x32x16_bf16 v[18:33], v[180:183], v[164:167], v[18:33]
	v_mfma_f32_32x32x16_bf16 v[2:17], v[192:195], v[164:167], v[2:17]
	ds_read_b128 v[234:237], v83 offset:96
	ds_read2_b64 v[238:241], v96 offset0:36 offset1:37
	s_waitcnt lgkmcnt(2)
	v_mfma_f32_32x32x16_bf16 v[50:65], v[230:233], v[226:229], v[50:65]
	v_mfma_f32_32x32x16_bf16 v[34:49], v[92:95], v[226:229], v[34:49]
	v_mfma_f32_32x32x16_bf16 v[18:33], v[168:171], v[226:229], v[18:33]
	v_mfma_f32_32x32x16_bf16 v[2:17], v[172:175], v[226:229], v[2:17]
	s_waitcnt lgkmcnt(0)
	v_mfma_f32_32x32x16_bf16 v[50:65], v[238:241], v[234:237], v[50:65]
	v_mfma_f32_32x32x16_bf16 v[34:49], v[160:163], v[234:237], v[34:49]
	v_mfma_f32_32x32x16_bf16 v[18:33], v[176:179], v[234:237], v[18:33]
	v_mfma_f32_32x32x16_bf16 v[2:17], v[180:183], v[234:237], v[2:17]
	s_cbranch_scc1 .LBB0_330
	s_waitcnt vmcnt(3)
	ds_write_b128 v159, v[66:69] offset:20736
	s_waitcnt vmcnt(2)
	ds_write_b128 v159, v[70:73] offset:24960
	s_waitcnt vmcnt(1)
	ds_write_b128 v159, v[74:77] offset:29184
	s_waitcnt vmcnt(0)
	ds_write_b128 v159, v[78:81] offset:33408
	s_waitcnt lgkmcnt(0)
	s_barrier
	global_load_dwordx4 v[66:69], v[84:85], off offset:2560
	global_load_dwordx4 v[70:73], v[86:87], off offset:2560
	global_load_dwordx4 v[74:77], v[88:89], off offset:2560
	global_load_dwordx4 v[78:81], v[90:91], off offset:2560
	s_mov_b32 s13, 0
; #define GAS __attribute__((address_space(1)))
; DI f32x16 mfma32(bf16x8 a, bf16x8 b, f32x16 c) { return __builtin_amdgcn_mfma_f32_32x32x16_bf16(a, b, c, 0, 0, 0); }
; DI void hyena_item(char* smem, const bf16_t* __restrict__ zin, const bf16_t* __restrict__ xg, const bf16_t* __restrict__ arr, float bias, bf16_t* __restrict__ zout, int tq, int tid) {
;     ...
;   for (int pnl = 0; pnl < 8; ++pnl) {
;     const char* zs = smem + ZOFF + (pnl & 1) * ZPB;
;     const bool more = (pnl + 1 < 8);
;     if (more) {
; #pragma unroll
;       for (int i = 0; i < 4; ++i) zr[i] = *(const GAS u32x4*)(zin + (size_t)(zb + 8 * i) * 2048 + (pnl + 1) * 256 + zc * 8);
;     }
;     __builtin_amdgcn_sched_barrier(0);
; #pragma unroll 4
;     for (int sc = 0; sc < 16; ++sc) {
;       const bf16x8 zf = *(const bf16x8*)(zs + r * ZSB + sc * 32 + h * 16);
;       const char* gp = gbase + (pnl * 256 + sc * 16) * 2;
; #pragma unroll
;       for (int i = 0; i < 4; ++i) {
;         const s16x4 g0 = *(const s16x4*)(gp - 64 * i), g1 = *(const s16x4*)(gp - 64 * i + 8);
;         const bf16x8 gf = __builtin_shufflevector(g0, g1, 0, 1, 2, 3, 4, 5, 6, 7);
;         acc[i] = mfma32(gf, zf, acc[i]);
;       }
;     }
;     if (more) {
;       char* zn = smem + ZOFF + ((pnl + 1) & 1) * ZPB;
; #pragma unroll
;       for (int i = 0; i < 4; ++i) *(u32x4*)(zn + (zb + 8 * i) * ZSB + zc * 16) = zr[i];
;     }
;     __syncthreads();
;   }
.LBB0_332:
	v_add_u32_e32 v96, s13, v153
	v_add_u32_e32 v83, s13, v147
	ds_read2_b64 v[92:95], v96 offset0:24 offset1:25
	ds_read_b128 v[160:163], v83
	ds_read_b128 v[164:167], v83 offset:32
	ds_read2_b64 v[168:171], v96 offset0:16 offset1:17
	ds_read2_b64 v[172:175], v96 offset0:8 offset1:9
	ds_read2_b64 v[176:179], v96 offset1:1
	s_waitcnt lgkmcnt(4)
	v_mfma_f32_32x32x16_bf16 v[50:65], v[92:95], v[160:163], v[50:65]
	ds_read2_b64 v[180:183], v96 offset0:12 offset1:13
	ds_read2_b64 v[192:195], v96 offset0:4 offset1:5
	s_addk_i32 s13, 0x80
	s_cmpk_lg_i32 s13, 0x200
	s_waitcnt lgkmcnt(4)
	v_mfma_f32_32x32x16_bf16 v[34:49], v[168:171], v[160:163], v[34:49]
	s_waitcnt lgkmcnt(3)
	v_mfma_f32_32x32x16_bf16 v[18:33], v[172:175], v[160:163], v[18:33]
	s_waitcnt lgkmcnt(2)
	v_mfma_f32_32x32x16_bf16 v[2:17], v[176:179], v[160:163], v[2:17]
	ds_read2_b64 v[160:163], v96 offset0:28 offset1:29
	ds_read2_b64 v[176:179], v96 offset0:20 offset1:21
	ds_read_b128 v[226:229], v83 offset:64
	ds_read2_b64 v[230:233], v96 offset0:32 offset1:33
	s_waitcnt lgkmcnt(3)
	v_mfma_f32_32x32x16_bf16 v[50:65], v[160:163], v[164:167], v[50:65]
	s_waitcnt lgkmcnt(2)
	v_mfma_f32_32x32x16_bf16 v[34:49], v[176:179], v[164:167], v[34:49]
	v_mfma_f32_32x32x16_bf16 v[18:33], v[180:183], v[164:167], v[18:33]
	v_mfma_f32_32x32x16_bf16 v[2:17], v[192:195], v[164:167], v[2:17]
	ds_read_b128 v[234:237], v83 offset:96
	ds_read2_b64 v[238:241], v96 offset0:36 offset1:37
	s_waitcnt lgkmcnt(2)
	v_mfma_f32_32x32x16_bf16 v[50:65], v[230:233], v[226:229], v[50:65]
	v_mfma_f32_32x32x16_bf16 v[34:49], v[92:95], v[226:229], v[34:49]
	v_mfma_f32_32x32x16_bf16 v[18:33], v[168:171], v[226:229], v[18:33]
	v_mfma_f32_32x32x16_bf16 v[2:17], v[172:175], v[226:229], v[2:17]
	s_waitcnt lgkmcnt(0)
	v_mfma_f32_32x32x16_bf16 v[50:65], v[238:241], v[234:237], v[50:65]
	v_mfma_f32_32x32x16_bf16 v[34:49], v[160:163], v[234:237], v[34:49]
	v_mfma_f32_32x32x16_bf16 v[18:33], v[176:179], v[234:237], v[18:33]
	v_mfma_f32_32x32x16_bf16 v[2:17], v[180:183], v[234:237], v[2:17]
	s_cbranch_scc1 .LBB0_332
	s_waitcnt vmcnt(3)
	ds_write_b128 v159, v[66:69] offset:37632
	s_waitcnt vmcnt(2)
	ds_write_b128 v159, v[70:73] offset:41856
	s_waitcnt vmcnt(1)
	ds_write_b128 v159, v[74:77] offset:46080
	s_waitcnt vmcnt(0)
	ds_write_b128 v159, v[78:81] offset:50304
	s_waitcnt lgkmcnt(0)
	s_barrier
	global_load_dwordx4 v[66:69], v[84:85], off offset:3072
	global_load_dwordx4 v[70:73], v[86:87], off offset:3072
	global_load_dwordx4 v[74:77], v[88:89], off offset:3072
	global_load_dwordx4 v[78:81], v[90:91], off offset:3072
	s_mov_b32 s13, 0
.LBB0_334:
	v_add_u32_e32 v96, s13, v154
	v_add_u32_e32 v83, s13, v150
	ds_read2_b64 v[92:95], v96 offset0:24 offset1:25
	ds_read_b128 v[160:163], v83
	ds_read_b128 v[164:167], v83 offset:32
	ds_read2_b64 v[168:171], v96 offset0:16 offset1:17
	ds_read2_b64 v[172:175], v96 offset0:8 offset1:9
	ds_read2_b64 v[176:179], v96 offset1:1
	s_waitcnt lgkmcnt(4)
	v_mfma_f32_32x32x16_bf16 v[50:65], v[92:95], v[160:163], v[50:65]
	ds_read2_b64 v[180:183], v96 offset0:12 offset1:13
	ds_read2_b64 v[192:195], v96 offset0:4 offset1:5
	s_addk_i32 s13, 0x80
	s_cmpk_lg_i32 s13, 0x200
	s_waitcnt lgkmcnt(4)
	v_mfma_f32_32x32x16_bf16 v[34:49], v[168:171], v[160:163], v[34:49]
	s_waitcnt lgkmcnt(3)
	v_mfma_f32_32x32x16_bf16 v[18:33], v[172:175], v[160:163], v[18:33]
	s_waitcnt lgkmcnt(2)
	v_mfma_f32_32x32x16_bf16 v[2:17], v[176:179], v[160:163], v[2:17]
	ds_read2_b64 v[160:163], v96 offset0:28 offset1:29
	ds_read2_b64 v[176:179], v96 offset0:20 offset1:21
	ds_read_b128 v[226:229], v83 offset:64
	ds_read2_b64 v[230:233], v96 offset0:32 offset1:33
	s_waitcnt lgkmcnt(3)
	v_mfma_f32_32x32x16_bf16 v[50:65], v[160:163], v[164:167], v[50:65]
	s_waitcnt lgkmcnt(2)
	v_mfma_f32_32x32x16_bf16 v[34:49], v[176:179], v[164:167], v[34:49]
	v_mfma_f32_32x32x16_bf16 v[18:33], v[180:183], v[164:167], v[18:33]
	v_mfma_f32_32x32x16_bf16 v[2:17], v[192:195], v[164:167], v[2:17]
	ds_read_b128 v[234:237], v83 offset:96
	ds_read2_b64 v[238:241], v96 offset0:36 offset1:37
	s_waitcnt lgkmcnt(2)
	v_mfma_f32_32x32x16_bf16 v[50:65], v[230:233], v[226:229], v[50:65]
	v_mfma_f32_32x32x16_bf16 v[34:49], v[92:95], v[226:229], v[34:49]
	v_mfma_f32_32x32x16_bf16 v[18:33], v[168:171], v[226:229], v[18:33]
	v_mfma_f32_32x32x16_bf16 v[2:17], v[172:175], v[226:229], v[2:17]
	s_waitcnt lgkmcnt(0)
	v_mfma_f32_32x32x16_bf16 v[50:65], v[238:241], v[234:237], v[50:65]
	v_mfma_f32_32x32x16_bf16 v[34:49], v[160:163], v[234:237], v[34:49]
	v_mfma_f32_32x32x16_bf16 v[18:33], v[176:179], v[234:237], v[18:33]
	v_mfma_f32_32x32x16_bf16 v[2:17], v[180:183], v[234:237], v[2:17]
	s_cbranch_scc1 .LBB0_334
	s_waitcnt vmcnt(3)
	ds_write_b128 v159, v[66:69] offset:20736
	s_waitcnt vmcnt(2)
	ds_write_b128 v159, v[70:73] offset:24960
	s_waitcnt vmcnt(1)
	ds_write_b128 v159, v[74:77] offset:29184
	s_waitcnt vmcnt(0)
	ds_write_b128 v159, v[78:81] offset:33408
	s_waitcnt lgkmcnt(0)
	s_barrier
	global_load_dwordx4 v[66:69], v[84:85], off offset:3584
	global_load_dwordx4 v[70:73], v[86:87], off offset:3584
	global_load_dwordx4 v[74:77], v[88:89], off offset:3584
	global_load_dwordx4 v[78:81], v[90:91], off offset:3584
	s_mov_b32 s13, 0
; #define GAS __attribute__((address_space(1)))
; DI f32x16 mfma32(bf16x8 a, bf16x8 b, f32x16 c) { return __builtin_amdgcn_mfma_f32_32x32x16_bf16(a, b, c, 0, 0, 0); }
; DI void hyena_item(char* smem, const bf16_t* __restrict__ zin, const bf16_t* __restrict__ xg, const bf16_t* __restrict__ arr, float bias, bf16_t* __restrict__ zout, int tq, int tid) {
;     ...
;   for (int pnl = 0; pnl < 8; ++pnl) {
;     const char* zs = smem + ZOFF + (pnl & 1) * ZPB;
;     const bool more = (pnl + 1 < 8);
;     if (more) {
; #pragma unroll
;       for (int i = 0; i < 4; ++i) zr[i] = *(const GAS u32x4*)(zin + (size_t)(zb + 8 * i) * 2048 + (pnl + 1) * 256 + zc * 8);
;     }
;     __builtin_amdgcn_sched_barrier(0);
; #pragma unroll 4
;     for (int sc = 0; sc < 16; ++sc) {
;       const bf16x8 zf = *(const bf16x8*)(zs + r * ZSB + sc * 32 + h * 16);
;       const char* gp = gbase + (pnl * 256 + sc * 16) * 2;
; #pragma unroll
;       for (int i = 0; i < 4; ++i) {
;         const s16x4 g0 = *(const s16x4*)(gp - 64 * i), g1 = *(const s16x4*)(gp - 64 * i + 8);
;         const bf16x8 gf = __builtin_shufflevector(g0, g1, 0, 1, 2, 3, 4, 5, 6, 7);
;         acc[i] = mfma32(gf, zf, acc[i]);
;       }
;     }
;     if (more) {
;       char* zn = smem + ZOFF + ((pnl + 1) & 1) * ZPB;
; #pragma unroll
;       for (int i = 0; i < 4; ++i) *(u32x4*)(zn + (zb + 8 * i) * ZSB + zc * 16) = zr[i];
;     }
;     __syncthreads();
;   }
.LBB0_336:
	v_add_u32_e32 v96, s13, v155
	v_add_u32_e32 v83, s13, v147
	ds_read2_b64 v[84:87], v96 offset0:24 offset1:25
	ds_read_b128 v[88:91], v83
	ds_read_b128 v[92:95], v83 offset:32
	ds_read2_b64 v[160:163], v96 offset0:16 offset1:17
	ds_read2_b64 v[164:167], v96 offset0:8 offset1:9
	ds_read2_b64 v[168:171], v96 offset1:1
	s_waitcnt lgkmcnt(4)
	v_mfma_f32_32x32x16_bf16 v[50:65], v[84:87], v[88:91], v[50:65]
	ds_read2_b64 v[172:175], v96 offset0:12 offset1:13
	ds_read2_b64 v[176:179], v96 offset0:4 offset1:5
	s_addk_i32 s13, 0x80
	s_cmpk_lg_i32 s13, 0x200
	s_waitcnt lgkmcnt(4)
	v_mfma_f32_32x32x16_bf16 v[34:49], v[160:163], v[88:91], v[34:49]
	s_waitcnt lgkmcnt(3)
	v_mfma_f32_32x32x16_bf16 v[18:33], v[164:167], v[88:91], v[18:33]
	s_waitcnt lgkmcnt(2)
	v_mfma_f32_32x32x16_bf16 v[2:17], v[168:171], v[88:91], v[2:17]
	ds_read2_b64 v[88:91], v96 offset0:28 offset1:29
	ds_read2_b64 v[168:171], v96 offset0:20 offset1:21
	ds_read_b128 v[226:229], v83 offset:64
	ds_read2_b64 v[230:233], v96 offset0:32 offset1:33
	s_waitcnt lgkmcnt(3)
	v_mfma_f32_32x32x16_bf16 v[50:65], v[88:91], v[92:95], v[50:65]
	s_waitcnt lgkmcnt(2)
	v_mfma_f32_32x32x16_bf16 v[34:49], v[168:171], v[92:95], v[34:49]
	v_mfma_f32_32x32x16_bf16 v[18:33], v[172:175], v[92:95], v[18:33]
	v_mfma_f32_32x32x16_bf16 v[2:17], v[176:179], v[92:95], v[2:17]
	ds_read_b128 v[234:237], v83 offset:96
	ds_read2_b64 v[238:241], v96 offset0:36 offset1:37
	s_waitcnt lgkmcnt(2)
	v_mfma_f32_32x32x16_bf16 v[50:65], v[230:233], v[226:229], v[50:65]
	v_mfma_f32_32x32x16_bf16 v[34:49], v[84:87], v[226:229], v[34:49]
	v_mfma_f32_32x32x16_bf16 v[18:33], v[160:163], v[226:229], v[18:33]
	v_mfma_f32_32x32x16_bf16 v[2:17], v[164:167], v[226:229], v[2:17]
	s_waitcnt lgkmcnt(0)
	v_mfma_f32_32x32x16_bf16 v[50:65], v[238:241], v[234:237], v[50:65]
	v_mfma_f32_32x32x16_bf16 v[34:49], v[88:91], v[234:237], v[34:49]
	v_mfma_f32_32x32x16_bf16 v[18:33], v[168:171], v[234:237], v[18:33]
	v_mfma_f32_32x32x16_bf16 v[2:17], v[172:175], v[234:237], v[2:17]
	s_cbranch_scc1 .LBB0_336
	s_waitcnt vmcnt(3)
	ds_write_b128 v159, v[66:69] offset:37632
	s_waitcnt vmcnt(2)
	ds_write_b128 v159, v[70:73] offset:41856
	s_waitcnt vmcnt(1)
	ds_write_b128 v159, v[74:77] offset:46080
	s_waitcnt vmcnt(0)
	ds_write_b128 v159, v[78:81] offset:50304
	s_waitcnt lgkmcnt(0)
	s_barrier
	s_mov_b32 s13, 0
.LBB0_338:
	v_add_u32_e32 v96, s13, v156
	v_add_u32_e32 v83, s13, v150
	ds_read2_b64 v[66:69], v96 offset0:24 offset1:25
	ds_read_b128 v[70:73], v83
	ds_read_b128 v[74:77], v83 offset:32
	ds_read2_b64 v[78:81], v96 offset0:16 offset1:17
	ds_read2_b64 v[84:87], v96 offset0:8 offset1:9
	ds_read2_b64 v[88:91], v96 offset1:1
	s_waitcnt lgkmcnt(4)
	v_mfma_f32_32x32x16_bf16 v[50:65], v[66:69], v[70:73], v[50:65]
	ds_read2_b64 v[92:95], v96 offset0:12 offset1:13
	ds_read2_b64 v[160:163], v96 offset0:4 offset1:5
	s_addk_i32 s13, 0x80
	s_cmpk_lg_i32 s13, 0x200
	s_waitcnt lgkmcnt(4)
	v_mfma_f32_32x32x16_bf16 v[34:49], v[78:81], v[70:73], v[34:49]
	s_waitcnt lgkmcnt(3)
	v_mfma_f32_32x32x16_bf16 v[18:33], v[84:87], v[70:73], v[18:33]
	s_waitcnt lgkmcnt(2)
	v_mfma_f32_32x32x16_bf16 v[2:17], v[88:91], v[70:73], v[2:17]
	ds_read2_b64 v[70:73], v96 offset0:28 offset1:29
	ds_read2_b64 v[88:91], v96 offset0:20 offset1:21
	ds_read_b128 v[226:229], v83 offset:64
	ds_read2_b64 v[230:233], v96 offset0:32 offset1:33
	s_waitcnt lgkmcnt(3)
	v_mfma_f32_32x32x16_bf16 v[50:65], v[70:73], v[74:77], v[50:65]
	s_waitcnt lgkmcnt(2)
	v_mfma_f32_32x32x16_bf16 v[34:49], v[88:91], v[74:77], v[34:49]
	v_mfma_f32_32x32x16_bf16 v[18:33], v[92:95], v[74:77], v[18:33]
	v_mfma_f32_32x32x16_bf16 v[2:17], v[160:163], v[74:77], v[2:17]
	ds_read_b128 v[234:237], v83 offset:96
	ds_read2_b64 v[238:241], v96 offset0:36 offset1:37
	s_waitcnt lgkmcnt(2)
	v_mfma_f32_32x32x16_bf16 v[50:65], v[230:233], v[226:229], v[50:65]
	v_mfma_f32_32x32x16_bf16 v[34:49], v[66:69], v[226:229], v[34:49]
	v_mfma_f32_32x32x16_bf16 v[18:33], v[78:81], v[226:229], v[18:33]
	v_mfma_f32_32x32x16_bf16 v[2:17], v[84:87], v[226:229], v[2:17]
	s_waitcnt lgkmcnt(0)
	v_mfma_f32_32x32x16_bf16 v[50:65], v[238:241], v[234:237], v[50:65]
	v_mfma_f32_32x32x16_bf16 v[34:49], v[70:73], v[234:237], v[34:49]
	v_mfma_f32_32x32x16_bf16 v[18:33], v[88:91], v[234:237], v[18:33]
	v_mfma_f32_32x32x16_bf16 v[2:17], v[92:95], v[234:237], v[2:17]
	s_cbranch_scc1 .LBB0_338
	s_add_i32 s10, s53, s12
	v_add_u32_e32 v66, s62, v143
	s_ashr_i32 s11, s10, 31
	v_ashrrev_i32_e32 v67, 31, v66
	s_lshl_b64 s[10:11], s[10:11], 17
	v_lshl_add_u64 v[66:67], v[66:67], 0, v[116:117]
	s_add_u32 s10, s47, s10
	v_lshlrev_b64 v[70:71], 1, v[66:67]
	s_addc_u32 s11, s52, s11
	v_lshl_add_u64 v[68:69], s[14:15], 0, v[70:71]
	s_barrier
; #define GAS __attribute__((address_space(1)))
; DI unsigned pk2(float a, float b) { f32x2 v = {a, b}; bf2_t r = __builtin_convertvector(v, bf2_t); return __builtin_bit_cast(unsigned, r); }
; DI float bflo(unsigned w) { return __uint_as_float(w << 16); }
; DI float bfhi(unsigned w) { return __uint_as_float(w & 0xffff0000u); }
; DI void hyena_item(char* smem, const bf16_t* __restrict__ zin, const bf16_t* __restrict__ xg, const bf16_t* __restrict__ arr, float bias, bf16_t* __restrict__ zout, int tq, int tid) {
;     ...
; #pragma unroll
;   for (int i = 0; i < 4; ++i) {
;     const int t0 = 512 * tq + 128 * wid + 32 * i;
; #pragma unroll
;     for (int g = 0; g < 4; ++g) {
;       const size_t off = (size_t)r * 2048 + t0 + 8 * g + 4 * h;
;       const u32x2 zw = *(const GAS u32x2*)(zin + off), xw = *(const GAS u32x2*)(xg + off);
;       const float o0 = bflo(xw.x) * (acc[i][4 * g + 0] + bias * bflo(zw.x));
;       const float o1 = bfhi(xw.x) * (acc[i][4 * g + 1] + bias * bfhi(zw.x));
;       const float o2 = bflo(xw.y) * (acc[i][4 * g + 2] + bias * bflo(zw.y));
;       const float o3 = bfhi(xw.y) * (acc[i][4 * g + 3] + bias * bfhi(zw.y));
;       u32x2 w; w.x = pk2(o0, o1); w.y = pk2(o2, o3);
;       *(GAS u32x2*)(zout + off) = w;
;     }
;   }
	v_lshl_add_u64 v[66:67], s[10:11], 0, v[70:71]
	s_add_u32 s12, s59, s16
	s_addc_u32 s13, s60, s17
	s_mov_b64 s[10:11], 0xf0
	v_lshl_add_u64 v[84:85], s[12:13], 0, v[70:71]
	v_mbcnt_lo_u32_b32 v72, -1, 0
	v_mbcnt_hi_u32_b32 v72, -1, v72
	v_and_b32_e32 v72, 32, v72
	v_lshrrev_b32_e32 v72, 2, v72
	v_mov_b32_e32 v73, 0
	v_lshl_add_u64 v[68:69], v[68:69], 0, v[72:73]
	v_lshl_add_u64 v[66:67], v[66:67], 0, v[72:73]
	v_lshl_add_u64 v[86:87], v[84:85], 0, v[72:73]
	global_load_dwordx4 v[226:229], v[68:69], off
	global_load_dwordx4 v[230:233], v[66:67], off
	global_load_dwordx4 v[234:237], v[68:69], off offset:32
	global_load_dwordx4 v[238:241], v[66:67], off offset:32
	global_load_dwordx4 v[242:245], v[68:69], off offset:64
	global_load_dwordx4 v[246:249], v[66:67], off offset:64
	global_load_dwordx4 v[160:163], v[68:69], off offset:96
	global_load_dwordx4 v[88:91], v[66:67], off offset:96
	s_waitcnt vmcnt(6)
	v_permlane32_swap_b32_e32 v226, v228
	v_permlane32_swap_b32_e32 v227, v229
	v_permlane32_swap_b32_e32 v230, v232
	v_permlane32_swap_b32_e32 v231, v233
	v_lshlrev_b32_e32 v72, 16, v226
	v_and_b32_e32 v73, 0xffff0000, v226
	v_lshlrev_b32_e32 v74, 16, v227
	v_and_b32_e32 v75, 0xffff0000, v227
	v_lshlrev_b32_e32 v76, 16, v230
	v_and_b32_e32 v77, 0xffff0000, v230
	v_lshlrev_b32_e32 v78, 16, v231
	v_and_b32_e32 v79, 0xffff0000, v231
	v_fma_f32 v50, v82, v72, v50
	v_fma_f32 v51, v82, v73, v51
	v_fma_f32 v52, v82, v74, v52
	v_fma_f32 v53, v82, v75, v53
	v_mul_f32_e32 v50, v50, v76
	v_mul_f32_e32 v51, v51, v77
	v_mul_f32_e32 v52, v52, v78
	v_mul_f32_e32 v53, v53, v79
	v_cvt_pk_bf16_f32 v92, v50, v51
	v_cvt_pk_bf16_f32 v93, v52, v53
	v_lshlrev_b32_e32 v72, 16, v228
	v_and_b32_e32 v73, 0xffff0000, v228
	v_lshlrev_b32_e32 v74, 16, v229
	v_and_b32_e32 v75, 0xffff0000, v229
	v_lshlrev_b32_e32 v76, 16, v232
	v_and_b32_e32 v77, 0xffff0000, v232
	v_lshlrev_b32_e32 v78, 16, v233
	v_and_b32_e32 v79, 0xffff0000, v233
	v_fma_f32 v54, v82, v72, v54
	v_fma_f32 v55, v82, v73, v55
	v_fma_f32 v56, v82, v74, v56
	v_fma_f32 v57, v82, v75, v57
	v_mul_f32_e32 v54, v54, v76
	v_mul_f32_e32 v55, v55, v77
	v_mul_f32_e32 v56, v56, v78
	v_mul_f32_e32 v57, v57, v79
	v_cvt_pk_bf16_f32 v94, v54, v55
	v_cvt_pk_bf16_f32 v95, v56, v57
	s_nop 1
	v_permlane32_swap_b32_e32 v92, v94
	v_permlane32_swap_b32_e32 v93, v95
	global_store_dwordx4 v[86:87], v[92:95], off
	s_waitcnt vmcnt(5)
	v_permlane32_swap_b32_e32 v234, v236
	v_permlane32_swap_b32_e32 v235, v237
	v_permlane32_swap_b32_e32 v238, v240
	v_permlane32_swap_b32_e32 v239, v241
	v_lshlrev_b32_e32 v72, 16, v234
	v_and_b32_e32 v73, 0xffff0000, v234
	v_lshlrev_b32_e32 v74, 16, v235
	v_and_b32_e32 v75, 0xffff0000, v235
	v_lshlrev_b32_e32 v76, 16, v238
	v_and_b32_e32 v77, 0xffff0000, v238
	v_lshlrev_b32_e32 v78, 16, v239
	v_and_b32_e32 v79, 0xffff0000, v239
	v_fma_f32 v58, v82, v72, v58
	v_fma_f32 v59, v82, v73, v59
	v_fma_f32 v60, v82, v74, v60
	v_fma_f32 v61, v82, v75, v61
	v_mul_f32_e32 v58, v58, v76
	v_mul_f32_e32 v59, v59, v77
	v_mul_f32_e32 v60, v60, v78
	v_mul_f32_e32 v61, v61, v79
	v_cvt_pk_bf16_f32 v92, v58, v59
	v_cvt_pk_bf16_f32 v93, v60, v61
	v_lshlrev_b32_e32 v72, 16, v236
	v_and_b32_e32 v73, 0xffff0000, v236
	v_lshlrev_b32_e32 v74, 16, v237
	v_and_b32_e32 v75, 0xffff0000, v237
	v_lshlrev_b32_e32 v76, 16, v240
	v_and_b32_e32 v77, 0xffff0000, v240
	v_lshlrev_b32_e32 v78, 16, v241
	v_and_b32_e32 v79, 0xffff0000, v241
	v_fma_f32 v62, v82, v72, v62
	v_fma_f32 v63, v82, v73, v63
	v_fma_f32 v64, v82, v74, v64
	v_fma_f32 v65, v82, v75, v65
	v_mul_f32_e32 v62, v62, v76
	v_mul_f32_e32 v63, v63, v77
	v_mul_f32_e32 v64, v64, v78
	v_mul_f32_e32 v65, v65, v79
	v_cvt_pk_bf16_f32 v94, v62, v63
	v_cvt_pk_bf16_f32 v95, v64, v65
	s_nop 1
	v_permlane32_swap_b32_e32 v92, v94
	v_permlane32_swap_b32_e32 v93, v95
	global_store_dwordx4 v[86:87], v[92:95], off offset:32
	s_waitcnt vmcnt(4)
	v_permlane32_swap_b32_e32 v242, v244
	v_permlane32_swap_b32_e32 v243, v245
	v_permlane32_swap_b32_e32 v246, v248
	v_permlane32_swap_b32_e32 v247, v249
	v_lshlrev_b32_e32 v72, 16, v242
	v_and_b32_e32 v73, 0xffff0000, v242
	v_lshlrev_b32_e32 v74, 16, v243
	v_and_b32_e32 v75, 0xffff0000, v243
	v_lshlrev_b32_e32 v76, 16, v246
	v_and_b32_e32 v77, 0xffff0000, v246
	v_lshlrev_b32_e32 v78, 16, v247
	v_and_b32_e32 v79, 0xffff0000, v247
	v_fma_f32 v34, v82, v72, v34
	v_fma_f32 v35, v82, v73, v35
	v_fma_f32 v36, v82, v74, v36
	v_fma_f32 v37, v82, v75, v37
	v_mul_f32_e32 v34, v34, v76
	v_mul_f32_e32 v35, v35, v77
	v_mul_f32_e32 v36, v36, v78
	v_mul_f32_e32 v37, v37, v79
	v_cvt_pk_bf16_f32 v92, v34, v35
	v_cvt_pk_bf16_f32 v93, v36, v37
	v_lshlrev_b32_e32 v72, 16, v244
	v_and_b32_e32 v73, 0xffff0000, v244
	v_lshlrev_b32_e32 v74, 16, v245
	v_and_b32_e32 v75, 0xffff0000, v245
	v_lshlrev_b32_e32 v76, 16, v248
	v_and_b32_e32 v77, 0xffff0000, v248
	v_lshlrev_b32_e32 v78, 16, v249
	v_and_b32_e32 v79, 0xffff0000, v249
	v_fma_f32 v38, v82, v72, v38
	v_fma_f32 v39, v82, v73, v39
	v_fma_f32 v40, v82, v74, v40
	v_fma_f32 v41, v82, v75, v41
	v_mul_f32_e32 v38, v38, v76
	v_mul_f32_e32 v39, v39, v77
	v_mul_f32_e32 v40, v40, v78
	v_mul_f32_e32 v41, v41, v79
	v_cvt_pk_bf16_f32 v94, v38, v39
	v_cvt_pk_bf16_f32 v95, v40, v41
	s_nop 1
	v_permlane32_swap_b32_e32 v92, v94
	v_permlane32_swap_b32_e32 v93, v95
	global_store_dwordx4 v[86:87], v[92:95], off offset:64
	s_waitcnt vmcnt(3)
; #define GAS __attribute__((address_space(1)))
; DI unsigned pk2(float a, float b) { f32x2 v = {a, b}; bf2_t r = __builtin_convertvector(v, bf2_t); return __builtin_bit_cast(unsigned, r); }
; DI float bflo(unsigned w) { return __uint_as_float(w << 16); }
; DI float bfhi(unsigned w) { return __uint_as_float(w & 0xffff0000u); }
; DI void hyena_item(char* smem, const bf16_t* __restrict__ zin, const bf16_t* __restrict__ xg, const bf16_t* __restrict__ arr, float bias, bf16_t* __restrict__ zout, int tq, int tid) {
;     ...
; #pragma unroll
;   for (int i = 0; i < 4; ++i) {
;     const int t0 = 512 * tq + 128 * wid + 32 * i;
; #pragma unroll
;     for (int g = 0; g < 4; ++g) {
;       const size_t off = (size_t)r * 2048 + t0 + 8 * g + 4 * h;
;       const u32x2 zw = *(const GAS u32x2*)(zin + off), xw = *(const GAS u32x2*)(xg + off);
;       const float o0 = bflo(xw.x) * (acc[i][4 * g + 0] + bias * bflo(zw.x));
;       const float o1 = bfhi(xw.x) * (acc[i][4 * g + 1] + bias * bfhi(zw.x));
;       const float o2 = bflo(xw.y) * (acc[i][4 * g + 2] + bias * bflo(zw.y));
;       const float o3 = bfhi(xw.y) * (acc[i][4 * g + 3] + bias * bfhi(zw.y));
;       u32x2 w; w.x = pk2(o0, o1); w.y = pk2(o2, o3);
;       *(GAS u32x2*)(zout + off) = w;
;     }
;   }
	v_permlane32_swap_b32_e32 v160, v162
	v_permlane32_swap_b32_e32 v161, v163
	v_permlane32_swap_b32_e32 v88, v90
	v_permlane32_swap_b32_e32 v89, v91
	v_lshlrev_b32_e32 v72, 16, v160
	v_and_b32_e32 v73, 0xffff0000, v160
	v_lshlrev_b32_e32 v74, 16, v161
	v_and_b32_e32 v75, 0xffff0000, v161
	v_lshlrev_b32_e32 v76, 16, v88
	v_and_b32_e32 v77, 0xffff0000, v88
	v_lshlrev_b32_e32 v78, 16, v89
	v_and_b32_e32 v79, 0xffff0000, v89
	v_fma_f32 v42, v82, v72, v42
	v_fma_f32 v43, v82, v73, v43
	v_fma_f32 v44, v82, v74, v44
	v_fma_f32 v45, v82, v75, v45
	v_mul_f32_e32 v42, v42, v76
	v_mul_f32_e32 v43, v43, v77
	v_mul_f32_e32 v44, v44, v78
	v_mul_f32_e32 v45, v45, v79
	v_cvt_pk_bf16_f32 v92, v42, v43
	v_cvt_pk_bf16_f32 v93, v44, v45
	v_lshlrev_b32_e32 v72, 16, v162
	v_and_b32_e32 v73, 0xffff0000, v162
	v_lshlrev_b32_e32 v74, 16, v163
	v_and_b32_e32 v75, 0xffff0000, v163
	v_lshlrev_b32_e32 v76, 16, v90
	v_and_b32_e32 v77, 0xffff0000, v90
	v_lshlrev_b32_e32 v78, 16, v91
	v_and_b32_e32 v79, 0xffff0000, v91
	v_fma_f32 v46, v82, v72, v46
	v_fma_f32 v47, v82, v73, v47
	v_fma_f32 v48, v82, v74, v48
	v_fma_f32 v49, v82, v75, v49
	v_mul_f32_e32 v46, v46, v76
	v_mul_f32_e32 v47, v47, v77
	v_mul_f32_e32 v48, v48, v78
	v_mul_f32_e32 v49, v49, v79
	v_cvt_pk_bf16_f32 v94, v46, v47
	v_cvt_pk_bf16_f32 v95, v48, v49
	s_nop 1
	v_permlane32_swap_b32_e32 v92, v94
	v_permlane32_swap_b32_e32 v93, v95
	global_store_dwordx4 v[86:87], v[92:95], off offset:96
	global_load_dwordx4 v[226:229], v[68:69], off offset:128
	global_load_dwordx4 v[230:233], v[66:67], off offset:128
	global_load_dwordx4 v[234:237], v[68:69], off offset:160
	global_load_dwordx4 v[238:241], v[66:67], off offset:160
	global_load_dwordx4 v[242:245], v[68:69], off offset:192
	global_load_dwordx4 v[246:249], v[66:67], off offset:192
	global_load_dwordx4 v[160:163], v[68:69], off offset:224
	global_load_dwordx4 v[88:91], v[66:67], off offset:224
	s_waitcnt vmcnt(6)
	v_permlane32_swap_b32_e32 v226, v228
	v_permlane32_swap_b32_e32 v227, v229
	v_permlane32_swap_b32_e32 v230, v232
	v_permlane32_swap_b32_e32 v231, v233
	v_lshlrev_b32_e32 v72, 16, v226
	v_and_b32_e32 v73, 0xffff0000, v226
	v_lshlrev_b32_e32 v74, 16, v227
	v_and_b32_e32 v75, 0xffff0000, v227
	v_lshlrev_b32_e32 v76, 16, v230
	v_and_b32_e32 v77, 0xffff0000, v230
	v_lshlrev_b32_e32 v78, 16, v231
	v_and_b32_e32 v79, 0xffff0000, v231
	v_fma_f32 v18, v82, v72, v18
	v_fma_f32 v19, v82, v73, v19
	v_fma_f32 v20, v82, v74, v20
	v_fma_f32 v21, v82, v75, v21
	v_mul_f32_e32 v18, v18, v76
	v_mul_f32_e32 v19, v19, v77
	v_mul_f32_e32 v20, v20, v78
	v_mul_f32_e32 v21, v21, v79
	v_cvt_pk_bf16_f32 v92, v18, v19
	v_cvt_pk_bf16_f32 v93, v20, v21
	v_lshlrev_b32_e32 v72, 16, v228
	v_and_b32_e32 v73, 0xffff0000, v228
	v_lshlrev_b32_e32 v74, 16, v229
	v_and_b32_e32 v75, 0xffff0000, v229
	v_lshlrev_b32_e32 v76, 16, v232
	v_and_b32_e32 v77, 0xffff0000, v232
	v_lshlrev_b32_e32 v78, 16, v233
	v_and_b32_e32 v79, 0xffff0000, v233
	v_fma_f32 v22, v82, v72, v22
	v_fma_f32 v23, v82, v73, v23
	v_fma_f32 v24, v82, v74, v24
	v_fma_f32 v25, v82, v75, v25
	v_mul_f32_e32 v22, v22, v76
	v_mul_f32_e32 v23, v23, v77
	v_mul_f32_e32 v24, v24, v78
	v_mul_f32_e32 v25, v25, v79
	v_cvt_pk_bf16_f32 v94, v22, v23
	v_cvt_pk_bf16_f32 v95, v24, v25
	s_nop 1
	v_permlane32_swap_b32_e32 v92, v94
	v_permlane32_swap_b32_e32 v93, v95
	global_store_dwordx4 v[86:87], v[92:95], off offset:128
	s_waitcnt vmcnt(5)
; #define GAS __attribute__((address_space(1)))
; DI unsigned pk2(float a, float b) { f32x2 v = {a, b}; bf2_t r = __builtin_convertvector(v, bf2_t); return __builtin_bit_cast(unsigned, r); }
; DI float bflo(unsigned w) { return __uint_as_float(w << 16); }
; DI float bfhi(unsigned w) { return __uint_as_float(w & 0xffff0000u); }
; DI void hyena_item(char* smem, const bf16_t* __restrict__ zin, const bf16_t* __restrict__ xg, const bf16_t* __restrict__ arr, float bias, bf16_t* __restrict__ zout, int tq, int tid) {
;     ...
; #pragma unroll
;   for (int i = 0; i < 4; ++i) {
;     const int t0 = 512 * tq + 128 * wid + 32 * i;
; #pragma unroll
;     for (int g = 0; g < 4; ++g) {
;       const size_t off = (size_t)r * 2048 + t0 + 8 * g + 4 * h;
;       const u32x2 zw = *(const GAS u32x2*)(zin + off), xw = *(const GAS u32x2*)(xg + off);
;       const float o0 = bflo(xw.x) * (acc[i][4 * g + 0] + bias * bflo(zw.x));
;       const float o1 = bfhi(xw.x) * (acc[i][4 * g + 1] + bias * bfhi(zw.x));
;       const float o2 = bflo(xw.y) * (acc[i][4 * g + 2] + bias * bflo(zw.y));
;       const float o3 = bfhi(xw.y) * (acc[i][4 * g + 3] + bias * bfhi(zw.y));
;       u32x2 w; w.x = pk2(o0, o1); w.y = pk2(o2, o3);
;       *(GAS u32x2*)(zout + off) = w;
;     }
;   }
	v_permlane32_swap_b32_e32 v234, v236
	v_permlane32_swap_b32_e32 v235, v237
	v_permlane32_swap_b32_e32 v238, v240
	v_permlane32_swap_b32_e32 v239, v241
	v_lshlrev_b32_e32 v72, 16, v234
	v_and_b32_e32 v73, 0xffff0000, v234
	v_lshlrev_b32_e32 v74, 16, v235
	v_and_b32_e32 v75, 0xffff0000, v235
	v_lshlrev_b32_e32 v76, 16, v238
	v_and_b32_e32 v77, 0xffff0000, v238
	v_lshlrev_b32_e32 v78, 16, v239
	v_and_b32_e32 v79, 0xffff0000, v239
	v_fma_f32 v26, v82, v72, v26
	v_fma_f32 v27, v82, v73, v27
	v_fma_f32 v28, v82, v74, v28
	v_fma_f32 v29, v82, v75, v29
	v_mul_f32_e32 v26, v26, v76
	v_mul_f32_e32 v27, v27, v77
	v_mul_f32_e32 v28, v28, v78
	v_mul_f32_e32 v29, v29, v79
	v_cvt_pk_bf16_f32 v92, v26, v27
	v_cvt_pk_bf16_f32 v93, v28, v29
	v_lshlrev_b32_e32 v72, 16, v236
	v_and_b32_e32 v73, 0xffff0000, v236
	v_lshlrev_b32_e32 v74, 16, v237
	v_and_b32_e32 v75, 0xffff0000, v237
	v_lshlrev_b32_e32 v76, 16, v240
	v_and_b32_e32 v77, 0xffff0000, v240
	v_lshlrev_b32_e32 v78, 16, v241
	v_and_b32_e32 v79, 0xffff0000, v241
	v_fma_f32 v30, v82, v72, v30
	v_fma_f32 v31, v82, v73, v31
	v_fma_f32 v32, v82, v74, v32
	v_fma_f32 v33, v82, v75, v33
	v_mul_f32_e32 v30, v30, v76
	v_mul_f32_e32 v31, v31, v77
	v_mul_f32_e32 v32, v32, v78
	v_mul_f32_e32 v33, v33, v79
	v_cvt_pk_bf16_f32 v94, v30, v31
	v_cvt_pk_bf16_f32 v95, v32, v33
	s_nop 1
	v_permlane32_swap_b32_e32 v92, v94
	v_permlane32_swap_b32_e32 v93, v95
	global_store_dwordx4 v[86:87], v[92:95], off offset:160
	s_waitcnt vmcnt(4)
	v_permlane32_swap_b32_e32 v242, v244
	v_permlane32_swap_b32_e32 v243, v245
	v_permlane32_swap_b32_e32 v246, v248
	v_permlane32_swap_b32_e32 v247, v249
	v_lshlrev_b32_e32 v72, 16, v242
	v_and_b32_e32 v73, 0xffff0000, v242
	v_lshlrev_b32_e32 v74, 16, v243
	v_and_b32_e32 v75, 0xffff0000, v243
	v_lshlrev_b32_e32 v76, 16, v246
	v_and_b32_e32 v77, 0xffff0000, v246
	v_lshlrev_b32_e32 v78, 16, v247
	v_and_b32_e32 v79, 0xffff0000, v247
	v_fma_f32 v2, v82, v72, v2
	v_fma_f32 v3, v82, v73, v3
	v_fma_f32 v4, v82, v74, v4
	v_fma_f32 v5, v82, v75, v5
	v_mul_f32_e32 v2, v2, v76
	v_mul_f32_e32 v3, v3, v77
	v_mul_f32_e32 v4, v4, v78
	v_mul_f32_e32 v5, v5, v79
	v_cvt_pk_bf16_f32 v92, v2, v3
	v_cvt_pk_bf16_f32 v93, v4, v5
	v_lshlrev_b32_e32 v72, 16, v244
	v_and_b32_e32 v73, 0xffff0000, v244
	v_lshlrev_b32_e32 v74, 16, v245
	v_and_b32_e32 v75, 0xffff0000, v245
	v_lshlrev_b32_e32 v76, 16, v248
	v_and_b32_e32 v77, 0xffff0000, v248
	v_lshlrev_b32_e32 v78, 16, v249
	v_and_b32_e32 v79, 0xffff0000, v249
	v_fma_f32 v6, v82, v72, v6
	v_fma_f32 v7, v82, v73, v7
	v_fma_f32 v8, v82, v74, v8
	v_fma_f32 v9, v82, v75, v9
	v_mul_f32_e32 v6, v6, v76
	v_mul_f32_e32 v7, v7, v77
	v_mul_f32_e32 v8, v8, v78
	v_mul_f32_e32 v9, v9, v79
	v_cvt_pk_bf16_f32 v94, v6, v7
	v_cvt_pk_bf16_f32 v95, v8, v9
	s_nop 1
	v_permlane32_swap_b32_e32 v92, v94
	v_permlane32_swap_b32_e32 v93, v95
	global_store_dwordx4 v[86:87], v[92:95], off offset:192
	s_waitcnt vmcnt(3)
	v_permlane32_swap_b32_e32 v160, v162
	v_permlane32_swap_b32_e32 v161, v163
	v_permlane32_swap_b32_e32 v88, v90
	v_permlane32_swap_b32_e32 v89, v91
	v_lshlrev_b32_e32 v72, 16, v160
	v_and_b32_e32 v73, 0xffff0000, v160
	v_lshlrev_b32_e32 v74, 16, v161
	v_and_b32_e32 v75, 0xffff0000, v161
	v_lshlrev_b32_e32 v76, 16, v88
	v_and_b32_e32 v77, 0xffff0000, v88
	v_lshlrev_b32_e32 v78, 16, v89
	v_and_b32_e32 v79, 0xffff0000, v89
	v_fma_f32 v10, v82, v72, v10
	v_fma_f32 v11, v82, v73, v11
	v_fma_f32 v12, v82, v74, v12
	v_fma_f32 v13, v82, v75, v13
	v_mul_f32_e32 v10, v10, v76
	v_mul_f32_e32 v11, v11, v77
	v_mul_f32_e32 v12, v12, v78
	v_mul_f32_e32 v13, v13, v79
	v_cvt_pk_bf16_f32 v92, v10, v11
	v_cvt_pk_bf16_f32 v93, v12, v13
	v_lshlrev_b32_e32 v72, 16, v162
	v_and_b32_e32 v73, 0xffff0000, v162
	v_lshlrev_b32_e32 v74, 16, v163
	v_and_b32_e32 v75, 0xffff0000, v163
	v_lshlrev_b32_e32 v76, 16, v90
	v_and_b32_e32 v77, 0xffff0000, v90
	v_lshlrev_b32_e32 v78, 16, v91
	v_and_b32_e32 v79, 0xffff0000, v91
	v_fma_f32 v14, v82, v72, v14
	v_fma_f32 v15, v82, v73, v15
	v_fma_f32 v16, v82, v74, v16
	v_fma_f32 v17, v82, v75, v17
	v_mul_f32_e32 v14, v14, v76
	v_mul_f32_e32 v15, v15, v77
	v_mul_f32_e32 v16, v16, v78
	v_mul_f32_e32 v17, v17, v79
	v_cvt_pk_bf16_f32 v94, v14, v15
	v_cvt_pk_bf16_f32 v95, v16, v17
	v_mov_b32_e32 v2, v94
	v_mov_b32_e32 v3, v95
	s_nop 1
	v_permlane32_swap_b32_e32 v92, v94
	v_permlane32_swap_b32_e32 v93, v95
	global_store_dwordx4 v[86:87], v[92:95], off offset:224
	v_lshl_add_u64 v[4:5], v[84:85], 0, s[10:11]
	s_branch .LBB0_301
